# attention: PV split by key halves, softmax VALU interleaved under PV MFMAs; epilogue loads hoisted; P0 w_in transpose de-serialised
# speedup vs baseline: 1.0417x; 1.0198x over previous
.LBB0_532:
	s_add_i32 s60, s84, s83
	s_add_i32 s56, s60, 0x7c0
	s_cmp_gt_i32 s56, s79
	s_cbranch_scc1 .LBB0_541
	v_add_u32_e32 v16, v206, v205
	ds_read_b128 v[4:7], v16
	ds_read_b128 v[8:11], v16 offset:32
	v_add3_u32 v2, s84, v220, 64
	v_cvt_f32_i32_e32 v2, v2
	s_andn2_b64 vcc, exec, s[58:59]
	v_fma_f32 v2, v190, v2, -v185
	v_fma_f32 v82, 0, v190, v2
	v_add_f32_e32 v83, v190, v2
	v_pk_fma_f32 v[84:85], v[190:191], s[16:17], v[2:3] op_sel_hi:[1,1,0]
	v_pk_fma_f32 v[86:87], v[190:191], s[18:19], v[2:3] op_sel_hi:[1,1,0]
	v_pk_fma_f32 v[88:89], v[190:191], s[20:21], v[2:3] op_sel_hi:[1,1,0]
	v_pk_fma_f32 v[90:91], v[190:191], s[22:23], v[2:3] op_sel_hi:[1,1,0]
	v_pk_fma_f32 v[92:93], v[190:191], s[24:25], v[2:3] op_sel_hi:[1,1,0]
	v_pk_fma_f32 v[94:95], v[190:191], s[36:37], v[2:3] op_sel_hi:[1,1,0]
	v_pk_fma_f32 v[96:97], v[190:191], s[54:55], v[2:3] op_sel_hi:[1,1,0]
	v_add_f32_e32 v2, v219, v2
	v_fma_f32 v98, 0, v190, v2
	s_waitcnt lgkmcnt(1)
	v_mfma_f32_32x32x16_bf16 v[82:97], v[4:7], v[114:117], v[82:97]
	v_add_f32_e32 v99, v190, v2
	v_fma_f32 v100, v190, s16, v2
	v_fma_f32 v101, v191, s17, v2
	v_fma_f32 v102, v190, s18, v2
	v_fma_f32 v103, v191, s19, v2
	v_pk_fma_f32 v[104:105], v[190:191], s[20:21], v[2:3] op_sel_hi:[1,1,0]
	v_pk_fma_f32 v[106:107], v[190:191], s[22:23], v[2:3] op_sel_hi:[1,1,0]
	v_pk_fma_f32 v[108:109], v[190:191], s[24:25], v[2:3] op_sel_hi:[1,1,0]
	v_pk_fma_f32 v[110:111], v[190:191], s[36:37], v[2:3] op_sel_hi:[1,1,0]
	s_waitcnt lgkmcnt(0)
	v_mfma_f32_32x32x16_bf16 v[82:97], v[8:11], v[118:121], v[82:97]
	ds_read_b128 v[4:7], v16 offset:64
	ds_read_b128 v[8:11], v16 offset:96
	v_fma_f32 v112, v190, s54, v2
	v_fma_f32 v113, v191, s55, v2
	s_waitcnt lgkmcnt(1)
	v_mfma_f32_32x32x16_bf16 v[82:97], v[4:7], v[122:125], v[82:97]
	ds_read_b128 v[4:7], v16 offset:8704
	ds_read_b128 v[12:15], v16 offset:8736
	s_waitcnt lgkmcnt(1)
	v_mfma_f32_32x32x16_bf16 v[98:113], v[4:7], v[114:117], v[98:113]
	s_waitcnt lgkmcnt(0)
	v_mfma_f32_32x32x16_bf16 v[98:113], v[12:15], v[118:121], v[98:113]
	v_mfma_f32_32x32x16_bf16 v[82:97], v[8:11], v[126:129], v[82:97]
	ds_read_b128 v[4:7], v16 offset:8768
	ds_read_b128 v[224:227], v16 offset:8800
	ds_read_b64_tr_b16 v[12:13], v207 offset:17408
	ds_read_b64_tr_b16 v[14:15], v207 offset:19968
	ds_read_b64_tr_b16 v[8:9], v207 offset:22528
	ds_read_b64_tr_b16 v[10:11], v207 offset:25088
	s_waitcnt lgkmcnt(5)
	v_mfma_f32_32x32x16_bf16 v[98:113], v[4:7], v[122:125], v[98:113]
	ds_read_b64_tr_b16 v[162:163], v207 offset:17472
	ds_read_b64_tr_b16 v[164:165], v207 offset:20032
	ds_read_b64_tr_b16 v[4:5], v207 offset:22592
	ds_read_b64_tr_b16 v[6:7], v207 offset:25152
	s_waitcnt lgkmcnt(8)
	v_mfma_f32_32x32x16_bf16 v[98:113], v[224:227], v[126:129], v[98:113]
	s_cbranch_vccnz .LBB0_535
	v_add_u32_e32 v2, s84, v222
	v_add_u32_e32 v17, 0x7e0, v2
	v_add_u32_e32 v16, 0x7c0, v2
	v_cmp_le_i32_e32 vcc, v17, v184
	s_nop 6
	v_cndmask_b32_e32 v98, v217, v98, vcc
	v_cmp_lt_i32_e32 vcc, v16, v184
	s_nop 1
	v_cndmask_b32_e32 v83, v217, v83, vcc
	v_cmp_le_i32_e32 vcc, v16, v184
	v_add_u32_e32 v16, 0x7e1, v2
	s_nop 0
	v_cndmask_b32_e32 v82, v217, v82, vcc
	v_cmp_le_i32_e32 vcc, v16, v184
	v_add_u32_e32 v16, 0x7c2, v2
	s_nop 0
	v_cndmask_b32_e32 v99, v217, v99, vcc
	v_cmp_le_i32_e32 vcc, v16, v184
	v_add_u32_e32 v16, 0x7e2, v2
	s_nop 0
	v_cndmask_b32_e32 v84, v217, v84, vcc
	v_cmp_le_i32_e32 vcc, v16, v184
	v_add_u32_e32 v16, 0x7c3, v2
	s_nop 0
	v_cndmask_b32_e32 v100, v217, v100, vcc
	v_cmp_le_i32_e32 vcc, v16, v184
	v_add_u32_e32 v16, 0x7e3, v2
	s_nop 0
	v_cndmask_b32_e32 v85, v217, v85, vcc
	v_cmp_le_i32_e32 vcc, v16, v184
	v_add_u32_e32 v16, 0x7c8, v2
	s_nop 0
	v_cndmask_b32_e32 v101, v217, v101, vcc
	v_cmp_le_i32_e32 vcc, v16, v184
	v_add_u32_e32 v16, 0x7e8, v2
	s_nop 0
	v_cndmask_b32_e32 v86, v217, v86, vcc
	v_cmp_le_i32_e32 vcc, v16, v184
	v_add_u32_e32 v16, 0x7c9, v2
	s_nop 0
	v_cndmask_b32_e32 v102, v217, v102, vcc
	v_cmp_le_i32_e32 vcc, v16, v184
	v_add_u32_e32 v16, 0x7e9, v2
	s_nop 0
	v_cndmask_b32_e32 v87, v217, v87, vcc
	v_cmp_le_i32_e32 vcc, v16, v184
	v_add_u32_e32 v16, 0x7ca, v2
	s_nop 0
	v_cndmask_b32_e32 v103, v217, v103, vcc
	v_cmp_le_i32_e32 vcc, v16, v184
	v_add_u32_e32 v16, 0x7ea, v2
	s_nop 0
	v_cndmask_b32_e32 v88, v217, v88, vcc
	v_cmp_le_i32_e32 vcc, v16, v184
	v_add_u32_e32 v16, 0x7cb, v2
	s_nop 0
	v_cndmask_b32_e32 v104, v217, v104, vcc
	v_cmp_le_i32_e32 vcc, v16, v184
	v_add_u32_e32 v16, 0x7eb, v2
	s_nop 0
	v_cndmask_b32_e32 v89, v217, v89, vcc
	v_cmp_le_i32_e32 vcc, v16, v184
	v_add_u32_e32 v16, 0x7d0, v2
	s_nop 0
	v_cndmask_b32_e32 v105, v217, v105, vcc
	v_cmp_le_i32_e32 vcc, v16, v184
	v_add_u32_e32 v16, 0x7f0, v2
	s_nop 0
	v_cndmask_b32_e32 v90, v217, v90, vcc
	v_cmp_le_i32_e32 vcc, v16, v184
	v_add_u32_e32 v16, 0x7d1, v2
	s_nop 0
	v_cndmask_b32_e32 v106, v217, v106, vcc
	v_cmp_le_i32_e32 vcc, v16, v184
	v_add_u32_e32 v16, 0x7f1, v2
	s_nop 0
	v_cndmask_b32_e32 v91, v217, v91, vcc
	v_cmp_le_i32_e32 vcc, v16, v184
	v_add_u32_e32 v16, 0x7d2, v2
	s_nop 0
	v_cndmask_b32_e32 v107, v217, v107, vcc
	v_cmp_le_i32_e32 vcc, v16, v184
	v_add_u32_e32 v16, 0x7f2, v2
	s_nop 0
	v_cndmask_b32_e32 v92, v217, v92, vcc
	v_cmp_le_i32_e32 vcc, v16, v184
	v_add_u32_e32 v16, 0x7d3, v2
	s_nop 0
	v_cndmask_b32_e32 v108, v217, v108, vcc
	v_cmp_le_i32_e32 vcc, v16, v184
	v_add_u32_e32 v16, 0x7f3, v2
	s_nop 0
	v_cndmask_b32_e32 v93, v217, v93, vcc
	v_cmp_le_i32_e32 vcc, v16, v184
	v_add_u32_e32 v16, 0x7d8, v2
	s_nop 0
	v_cndmask_b32_e32 v109, v217, v109, vcc
	v_cmp_le_i32_e32 vcc, v16, v184
	v_add_u32_e32 v16, 0x7f8, v2
	s_nop 0
	v_cndmask_b32_e32 v94, v217, v94, vcc
	v_cmp_le_i32_e32 vcc, v16, v184
	v_add_u32_e32 v16, 0x7d9, v2
	s_nop 0
	v_cndmask_b32_e32 v110, v217, v110, vcc
	v_cmp_le_i32_e32 vcc, v16, v184
	v_add_u32_e32 v16, 0x7f9, v2
	s_nop 0
	v_cndmask_b32_e32 v95, v217, v95, vcc
	v_cmp_le_i32_e32 vcc, v16, v184
	v_add_u32_e32 v16, 0x7da, v2
	s_nop 0
	v_cndmask_b32_e32 v111, v217, v111, vcc
	v_cmp_le_i32_e32 vcc, v16, v184
	v_add_u32_e32 v16, 0x7fa, v2
	s_nop 0
	v_cndmask_b32_e32 v96, v217, v96, vcc
	v_cmp_le_i32_e32 vcc, v16, v184
	v_add_u32_e32 v16, 0x7db, v2
	v_add_u32_e32 v2, 0x7fb, v2
	v_cndmask_b32_e32 v112, v217, v112, vcc
	v_cmp_le_i32_e32 vcc, v16, v184
	s_nop 1
	v_cndmask_b32_e32 v97, v217, v97, vcc
	v_cmp_le_i32_e32 vcc, v2, v184
	s_nop 1
	v_cndmask_b32_e32 v113, v217, v113, vcc

.LBB0_540:
	v_exp_f32_e32 v82, v82
	v_exp_f32_e32 v83, v83
	v_exp_f32_e32 v84, v84
	v_exp_f32_e32 v85, v85
	ds_read_b64_tr_b16 v[240:241], v207 offset:17536
	ds_read_b64_tr_b16 v[242:243], v207 offset:20096
	ds_read_b64_tr_b16 v[244:245], v207 offset:22656
	ds_read_b64_tr_b16 v[246:247], v207 offset:25216
	ds_read_b64_tr_b16 v[248:249], v207 offset:17600
	ds_read_b64_tr_b16 v[250:251], v207 offset:20160
	ds_read_b64_tr_b16 v[252:253], v207 offset:22720
	ds_read_b64_tr_b16 v[254:255], v207 offset:25280
	v_exp_f32_e32 v86, v86
	v_exp_f32_e32 v87, v87
	v_exp_f32_e32 v88, v88
	v_exp_f32_e32 v89, v89
	v_exp_f32_e32 v90, v90
	v_exp_f32_e32 v91, v91
	v_exp_f32_e32 v92, v92
	v_exp_f32_e32 v93, v93
	v_exp_f32_e32 v94, v94
	v_exp_f32_e32 v95, v95
	v_exp_f32_e32 v96, v96
	v_exp_f32_e32 v97, v97
	v_cvt_pk_bf16_f32 v224, v82, v83
	v_cvt_pk_bf16_f32 v225, v84, v85
	v_cvt_pk_bf16_f32 v226, v86, v87
	v_cvt_pk_bf16_f32 v227, v88, v89
	v_cvt_pk_bf16_f32 v228, v90, v91
	v_cvt_pk_bf16_f32 v229, v92, v93
	v_cvt_pk_bf16_f32 v230, v94, v95
	v_cvt_pk_bf16_f32 v231, v96, v97
	s_waitcnt lgkmcnt(14)
	v_mfma_f32_32x32x16_bf16 v[66:81], v[12:15], v[224:227], v[66:81]
	v_exp_f32_e32 v98, v98
	v_exp_f32_e32 v99, v99
	v_add_f32_e32 v2, v82, v83
	s_waitcnt lgkmcnt(12)
	v_mfma_f32_32x32x16_bf16 v[66:81], v[8:11], v[228:231], v[66:81]
	v_exp_f32_e32 v100, v100
	v_exp_f32_e32 v101, v101
	v_cvt_pk_bf16_f32 v232, v98, v99
	v_add_f32_e32 v17, v84, v85
	ds_read_b64_tr_b16 v[12:13], v207 offset:27648
	ds_read_b64_tr_b16 v[14:15], v207 offset:30208
	ds_read_b64_tr_b16 v[8:9], v207 offset:32768
	ds_read_b64_tr_b16 v[10:11], v207 offset:35328
	s_waitcnt lgkmcnt(14)
	v_mfma_f32_32x32x16_bf16 v[50:65], v[162:165], v[224:227], v[50:65]
	v_exp_f32_e32 v102, v102
	v_exp_f32_e32 v103, v103
	v_cvt_pk_bf16_f32 v233, v100, v101
	v_add_f32_e32 v2, v2, v86
	s_waitcnt lgkmcnt(12)
	v_mfma_f32_32x32x16_bf16 v[50:65], v[4:7], v[228:231], v[50:65]
	v_exp_f32_e32 v104, v104
	v_exp_f32_e32 v105, v105
	v_cvt_pk_bf16_f32 v234, v102, v103
	v_add_f32_e32 v17, v17, v87
	ds_read_b64_tr_b16 v[162:163], v207 offset:27712
	ds_read_b64_tr_b16 v[164:165], v207 offset:30272
	ds_read_b64_tr_b16 v[4:5], v207 offset:32832
	ds_read_b64_tr_b16 v[6:7], v207 offset:35392
	s_waitcnt lgkmcnt(14)
	v_mfma_f32_32x32x16_bf16 v[34:49], v[240:243], v[224:227], v[34:49]
	v_exp_f32_e32 v106, v106
	v_exp_f32_e32 v107, v107
	v_cvt_pk_bf16_f32 v235, v104, v105
	v_add_f32_e32 v2, v2, v88
	s_waitcnt lgkmcnt(12)
	v_mfma_f32_32x32x16_bf16 v[34:49], v[244:247], v[228:231], v[34:49]
	v_exp_f32_e32 v108, v108
	v_exp_f32_e32 v109, v109
	v_cvt_pk_bf16_f32 v236, v106, v107
	v_add_f32_e32 v17, v17, v89
	ds_read_b64_tr_b16 v[240:241], v207 offset:27776
	ds_read_b64_tr_b16 v[242:243], v207 offset:30336
	ds_read_b64_tr_b16 v[244:245], v207 offset:32896
	ds_read_b64_tr_b16 v[246:247], v207 offset:35456
	s_waitcnt lgkmcnt(14)
	v_mfma_f32_32x32x16_bf16 v[18:33], v[248:251], v[224:227], v[18:33]
	v_exp_f32_e32 v110, v110
	v_exp_f32_e32 v111, v111
	v_cvt_pk_bf16_f32 v237, v108, v109
	v_add_f32_e32 v2, v2, v90
	s_waitcnt lgkmcnt(12)
	v_mfma_f32_32x32x16_bf16 v[18:33], v[252:255], v[228:231], v[18:33]
	v_exp_f32_e32 v112, v112
	v_exp_f32_e32 v113, v113
	v_cvt_pk_bf16_f32 v238, v110, v111
	v_add_f32_e32 v17, v17, v91
	ds_read_b64_tr_b16 v[248:249], v207 offset:27840
	ds_read_b64_tr_b16 v[250:251], v207 offset:30400
	ds_read_b64_tr_b16 v[252:253], v207 offset:32960
	ds_read_b64_tr_b16 v[254:255], v207 offset:35520
	v_cvt_pk_bf16_f32 v239, v112, v113
	s_waitcnt lgkmcnt(14)
	v_mfma_f32_32x32x16_bf16 v[66:81], v[12:15], v[232:235], v[66:81]
	v_add_f32_e32 v2, v2, v92
	v_add_f32_e32 v17, v17, v93
	v_add_f32_e32 v2, v2, v94
	v_add_f32_e32 v17, v17, v95
	s_waitcnt lgkmcnt(12)
	v_mfma_f32_32x32x16_bf16 v[66:81], v[8:11], v[236:239], v[66:81]
	v_add_f32_e32 v2, v2, v96
	v_add_f32_e32 v17, v17, v97
	v_add_f32_e32 v2, v2, v17
	v_add_f32_e32 v16, v98, v99
	s_waitcnt lgkmcnt(10)
	v_mfma_f32_32x32x16_bf16 v[50:65], v[162:165], v[232:235], v[50:65]
	v_add_f32_e32 v223, v100, v101
	v_add_f32_e32 v16, v16, v102
	v_add_f32_e32 v223, v223, v103
	v_add_f32_e32 v16, v16, v104
	s_waitcnt lgkmcnt(8)
	v_mfma_f32_32x32x16_bf16 v[50:65], v[4:7], v[236:239], v[50:65]
	v_add_f32_e32 v223, v223, v105
	v_add_f32_e32 v16, v16, v106
	v_add_f32_e32 v223, v223, v107
	v_add_f32_e32 v16, v16, v108
	s_waitcnt lgkmcnt(6)
	v_mfma_f32_32x32x16_bf16 v[34:49], v[240:243], v[232:235], v[34:49]
	s_mov_b64 s[58:59], 0
	v_add_f32_e32 v223, v223, v109
	v_add_f32_e32 v16, v16, v110
	v_add_f32_e32 v223, v223, v111
	v_add_f32_e32 v16, v16, v112
	s_waitcnt lgkmcnt(4)
	v_mfma_f32_32x32x16_bf16 v[34:49], v[244:247], v[236:239], v[34:49]
	v_add_f32_e32 v223, v223, v113
	v_add_f32_e32 v16, v16, v223
	v_add_f32_e32 v2, v2, v16
	v_add_f32_e32 v168, v168, v2
	s_waitcnt lgkmcnt(2)
	v_mfma_f32_32x32x16_bf16 v[18:33], v[248:251], v[232:235], v[18:33]
	s_waitcnt lgkmcnt(0)
	v_mfma_f32_32x32x16_bf16 v[18:33], v[252:255], v[236:239], v[18:33]

.LBB0_549:
	v_add_u32_e32 v16, v206, v205
	ds_read_b128 v[4:7], v16 offset:37888
	ds_read_b128 v[8:11], v16 offset:37920
	v_add_u32_e32 v2, s84, v220
	v_cvt_f32_i32_e32 v2, v2
	s_andn2_b64 vcc, exec, s[58:59]
	v_fma_f32 v2, v190, v2, -v185
	v_fma_f32 v82, 0, v190, v2
	v_add_f32_e32 v83, v190, v2
	v_pk_fma_f32 v[84:85], v[190:191], s[16:17], v[2:3] op_sel_hi:[1,1,0]
	v_pk_fma_f32 v[86:87], v[190:191], s[18:19], v[2:3] op_sel_hi:[1,1,0]
	v_pk_fma_f32 v[88:89], v[190:191], s[20:21], v[2:3] op_sel_hi:[1,1,0]
	v_pk_fma_f32 v[90:91], v[190:191], s[22:23], v[2:3] op_sel_hi:[1,1,0]
	v_pk_fma_f32 v[92:93], v[190:191], s[24:25], v[2:3] op_sel_hi:[1,1,0]
	v_pk_fma_f32 v[94:95], v[190:191], s[36:37], v[2:3] op_sel_hi:[1,1,0]
	v_pk_fma_f32 v[96:97], v[190:191], s[54:55], v[2:3] op_sel_hi:[1,1,0]
	v_add_f32_e32 v2, v219, v2
	v_fma_f32 v98, 0, v190, v2
	s_waitcnt lgkmcnt(1)
	v_mfma_f32_32x32x16_bf16 v[82:97], v[4:7], v[114:117], v[82:97]
	v_add_f32_e32 v99, v190, v2
	v_fma_f32 v100, v190, s16, v2
	v_fma_f32 v101, v191, s17, v2
	v_fma_f32 v102, v190, s18, v2
	v_fma_f32 v103, v191, s19, v2
	v_pk_fma_f32 v[104:105], v[190:191], s[20:21], v[2:3] op_sel_hi:[1,1,0]
	v_pk_fma_f32 v[106:107], v[190:191], s[22:23], v[2:3] op_sel_hi:[1,1,0]
	v_pk_fma_f32 v[108:109], v[190:191], s[24:25], v[2:3] op_sel_hi:[1,1,0]
	v_pk_fma_f32 v[110:111], v[190:191], s[36:37], v[2:3] op_sel_hi:[1,1,0]
	s_waitcnt lgkmcnt(0)
	v_mfma_f32_32x32x16_bf16 v[82:97], v[8:11], v[118:121], v[82:97]
	ds_read_b128 v[4:7], v16 offset:37952
	ds_read_b128 v[8:11], v16 offset:37984
	v_fma_f32 v112, v190, s54, v2
	v_fma_f32 v113, v191, s55, v2
	s_waitcnt lgkmcnt(1)
	v_mfma_f32_32x32x16_bf16 v[82:97], v[4:7], v[122:125], v[82:97]
	ds_read_b128 v[4:7], v16 offset:46592
	ds_read_b128 v[12:15], v16 offset:46624
	s_waitcnt lgkmcnt(1)
	v_mfma_f32_32x32x16_bf16 v[98:113], v[4:7], v[114:117], v[98:113]
	s_waitcnt lgkmcnt(0)
	v_mfma_f32_32x32x16_bf16 v[98:113], v[12:15], v[118:121], v[98:113]
	ds_read_b128 v[4:7], v16 offset:46656
	ds_read_b128 v[224:227], v16 offset:46688
	ds_read_b64_tr_b16 v[162:163], v210 offset:0
	ds_read_b64_tr_b16 v[164:165], v210 offset:2560
	ds_read_b64_tr_b16 v[12:13], v210 offset:5120
	ds_read_b64_tr_b16 v[14:15], v210 offset:7680
	s_waitcnt lgkmcnt(5)
	v_mfma_f32_32x32x16_bf16 v[98:113], v[4:7], v[122:125], v[98:113]
	v_mfma_f32_32x32x16_bf16 v[82:97], v[8:11], v[126:129], v[82:97]
	ds_read_b64_tr_b16 v[8:9], v210 offset:64
	ds_read_b64_tr_b16 v[10:11], v210 offset:2624
	ds_read_b64_tr_b16 v[4:5], v210 offset:5184
	ds_read_b64_tr_b16 v[6:7], v210 offset:7744
	s_waitcnt lgkmcnt(8)
	v_mfma_f32_32x32x16_bf16 v[98:113], v[224:227], v[126:129], v[98:113]
	s_cbranch_vccnz .LBB0_551
	v_add_u32_e32 v2, s84, v222
	v_add_u32_e32 v17, 0x7a0, v2
	v_add_u32_e32 v16, 0x780, v2
	v_cmp_le_i32_e32 vcc, v17, v184
	s_nop 6
	v_cndmask_b32_e32 v98, v217, v98, vcc
	v_cmp_lt_i32_e32 vcc, v16, v184
	s_nop 1
	v_cndmask_b32_e32 v83, v217, v83, vcc
	v_cmp_le_i32_e32 vcc, v16, v184
	v_add_u32_e32 v16, 0x7a1, v2
	s_nop 0
	v_cndmask_b32_e32 v82, v217, v82, vcc
	v_cmp_le_i32_e32 vcc, v16, v184
	v_add_u32_e32 v16, 0x782, v2
	s_nop 0
	v_cndmask_b32_e32 v99, v217, v99, vcc
	v_cmp_le_i32_e32 vcc, v16, v184
	v_add_u32_e32 v16, 0x7a2, v2
	s_nop 0
	v_cndmask_b32_e32 v84, v217, v84, vcc
	v_cmp_le_i32_e32 vcc, v16, v184
	v_add_u32_e32 v16, 0x783, v2
	s_nop 0
	v_cndmask_b32_e32 v100, v217, v100, vcc
	v_cmp_le_i32_e32 vcc, v16, v184
	v_add_u32_e32 v16, 0x7a3, v2
	s_nop 0
	v_cndmask_b32_e32 v85, v217, v85, vcc
	v_cmp_le_i32_e32 vcc, v16, v184
	v_add_u32_e32 v16, 0x788, v2
	s_nop 0
	v_cndmask_b32_e32 v101, v217, v101, vcc
	v_cmp_le_i32_e32 vcc, v16, v184
	v_add_u32_e32 v16, 0x7a8, v2
	s_nop 0
	v_cndmask_b32_e32 v86, v217, v86, vcc
	v_cmp_le_i32_e32 vcc, v16, v184
	v_add_u32_e32 v16, 0x789, v2
	s_nop 0
	v_cndmask_b32_e32 v102, v217, v102, vcc
	v_cmp_le_i32_e32 vcc, v16, v184
	v_add_u32_e32 v16, 0x7a9, v2
	s_nop 0
	v_cndmask_b32_e32 v87, v217, v87, vcc
	v_cmp_le_i32_e32 vcc, v16, v184
	v_add_u32_e32 v16, 0x78a, v2
	s_nop 0
	v_cndmask_b32_e32 v103, v217, v103, vcc
	v_cmp_le_i32_e32 vcc, v16, v184
	v_add_u32_e32 v16, 0x7aa, v2
	s_nop 0
	v_cndmask_b32_e32 v88, v217, v88, vcc
	v_cmp_le_i32_e32 vcc, v16, v184
	v_add_u32_e32 v16, 0x78b, v2
	s_nop 0
	v_cndmask_b32_e32 v104, v217, v104, vcc
	v_cmp_le_i32_e32 vcc, v16, v184
	v_add_u32_e32 v16, 0x7ab, v2
	s_nop 0
	v_cndmask_b32_e32 v89, v217, v89, vcc
	v_cmp_le_i32_e32 vcc, v16, v184
	v_add_u32_e32 v16, 0x790, v2
	s_nop 0
	v_cndmask_b32_e32 v105, v217, v105, vcc
	v_cmp_le_i32_e32 vcc, v16, v184
	v_add_u32_e32 v16, 0x7b0, v2
	s_nop 0
	v_cndmask_b32_e32 v90, v217, v90, vcc
	v_cmp_le_i32_e32 vcc, v16, v184
	v_add_u32_e32 v16, 0x791, v2
	s_nop 0
	v_cndmask_b32_e32 v106, v217, v106, vcc
	v_cmp_le_i32_e32 vcc, v16, v184
	v_add_u32_e32 v16, 0x7b1, v2
	s_nop 0
	v_cndmask_b32_e32 v91, v217, v91, vcc
	v_cmp_le_i32_e32 vcc, v16, v184
	v_add_u32_e32 v16, 0x792, v2
	s_nop 0
	v_cndmask_b32_e32 v107, v217, v107, vcc
	v_cmp_le_i32_e32 vcc, v16, v184
	v_add_u32_e32 v16, 0x7b2, v2
	s_nop 0
	v_cndmask_b32_e32 v92, v217, v92, vcc
	v_cmp_le_i32_e32 vcc, v16, v184
	v_add_u32_e32 v16, 0x793, v2
	s_nop 0
	v_cndmask_b32_e32 v108, v217, v108, vcc
	v_cmp_le_i32_e32 vcc, v16, v184
	v_add_u32_e32 v16, 0x7b3, v2
	s_nop 0
	v_cndmask_b32_e32 v93, v217, v93, vcc
	v_cmp_le_i32_e32 vcc, v16, v184
	v_add_u32_e32 v16, 0x798, v2
	s_nop 0
	v_cndmask_b32_e32 v109, v217, v109, vcc
	v_cmp_le_i32_e32 vcc, v16, v184
	v_add_u32_e32 v16, 0x7b8, v2
	s_nop 0
	v_cndmask_b32_e32 v94, v217, v94, vcc
	v_cmp_le_i32_e32 vcc, v16, v184
	v_add_u32_e32 v16, 0x799, v2
	s_nop 0
	v_cndmask_b32_e32 v110, v217, v110, vcc
	v_cmp_le_i32_e32 vcc, v16, v184
	v_add_u32_e32 v16, 0x7b9, v2
	s_nop 0
	v_cndmask_b32_e32 v95, v217, v95, vcc
	v_cmp_le_i32_e32 vcc, v16, v184
	v_add_u32_e32 v16, 0x79a, v2
	s_nop 0
	v_cndmask_b32_e32 v111, v217, v111, vcc
	v_cmp_le_i32_e32 vcc, v16, v184
	v_add_u32_e32 v16, 0x7ba, v2
	s_nop 0
	v_cndmask_b32_e32 v96, v217, v96, vcc
	v_cmp_le_i32_e32 vcc, v16, v184
	v_add_u32_e32 v16, 0x79b, v2
	v_add_u32_e32 v2, 0x7bb, v2
	v_cndmask_b32_e32 v112, v217, v112, vcc
	v_cmp_le_i32_e32 vcc, v16, v184
	s_nop 1
	v_cndmask_b32_e32 v97, v217, v97, vcc
	v_cmp_le_i32_e32 vcc, v2, v184
	s_nop 1
	v_cndmask_b32_e32 v113, v217, v113, vcc

.LBB0_556:
	s_nop 2
	v_exp_f32_e32 v82, v82
	v_exp_f32_e32 v83, v83
	v_exp_f32_e32 v84, v84
	v_exp_f32_e32 v85, v85
	ds_read_b64_tr_b16 v[240:241], v210 offset:128
	ds_read_b64_tr_b16 v[242:243], v210 offset:2688
	ds_read_b64_tr_b16 v[244:245], v210 offset:5248
	ds_read_b64_tr_b16 v[246:247], v210 offset:7808
	ds_read_b64_tr_b16 v[248:249], v210 offset:192
	ds_read_b64_tr_b16 v[250:251], v210 offset:2752
	ds_read_b64_tr_b16 v[252:253], v210 offset:5312
	ds_read_b64_tr_b16 v[254:255], v210 offset:7872
	v_exp_f32_e32 v86, v86
	v_exp_f32_e32 v87, v87
	v_exp_f32_e32 v88, v88
	v_exp_f32_e32 v89, v89
	v_exp_f32_e32 v90, v90
	v_exp_f32_e32 v91, v91
	v_exp_f32_e32 v92, v92
	v_exp_f32_e32 v93, v93
	v_exp_f32_e32 v94, v94
	v_exp_f32_e32 v95, v95
	v_exp_f32_e32 v96, v96
	v_exp_f32_e32 v97, v97
	v_cvt_pk_bf16_f32 v224, v82, v83
	v_cvt_pk_bf16_f32 v225, v84, v85
	v_cvt_pk_bf16_f32 v226, v86, v87
	v_cvt_pk_bf16_f32 v227, v88, v89
	v_cvt_pk_bf16_f32 v228, v90, v91
	v_cvt_pk_bf16_f32 v229, v92, v93
	v_cvt_pk_bf16_f32 v230, v94, v95
	v_cvt_pk_bf16_f32 v231, v96, v97
	s_waitcnt lgkmcnt(14)
	v_mfma_f32_32x32x16_bf16 v[66:81], v[162:165], v[224:227], v[66:81]
	v_exp_f32_e32 v98, v98
	v_exp_f32_e32 v99, v99
	v_add_f32_e32 v2, v82, v83
	s_waitcnt lgkmcnt(12)
	v_mfma_f32_32x32x16_bf16 v[66:81], v[12:15], v[228:231], v[66:81]
	v_exp_f32_e32 v100, v100
	v_exp_f32_e32 v101, v101
	v_cvt_pk_bf16_f32 v232, v98, v99
	v_add_f32_e32 v17, v84, v85
	ds_read_b64_tr_b16 v[162:163], v210 offset:10240
	ds_read_b64_tr_b16 v[164:165], v210 offset:12800
	ds_read_b64_tr_b16 v[12:13], v210 offset:15360
	ds_read_b64_tr_b16 v[14:15], v210 offset:17920
	s_waitcnt lgkmcnt(14)
	v_mfma_f32_32x32x16_bf16 v[50:65], v[8:11], v[224:227], v[50:65]
	v_exp_f32_e32 v102, v102
	v_exp_f32_e32 v103, v103
	v_cvt_pk_bf16_f32 v233, v100, v101
	v_add_f32_e32 v2, v2, v86
	s_waitcnt lgkmcnt(12)
	v_mfma_f32_32x32x16_bf16 v[50:65], v[4:7], v[228:231], v[50:65]
	v_exp_f32_e32 v104, v104
	v_exp_f32_e32 v105, v105
	v_cvt_pk_bf16_f32 v234, v102, v103
	v_add_f32_e32 v17, v17, v87
	ds_read_b64_tr_b16 v[8:9], v210 offset:10304
	ds_read_b64_tr_b16 v[10:11], v210 offset:12864
	ds_read_b64_tr_b16 v[4:5], v210 offset:15424
	ds_read_b64_tr_b16 v[6:7], v210 offset:17984
	s_waitcnt lgkmcnt(14)
	v_mfma_f32_32x32x16_bf16 v[34:49], v[240:243], v[224:227], v[34:49]
	v_exp_f32_e32 v106, v106
	v_exp_f32_e32 v107, v107
	v_cvt_pk_bf16_f32 v235, v104, v105
	v_add_f32_e32 v2, v2, v88
	s_waitcnt lgkmcnt(12)
	v_mfma_f32_32x32x16_bf16 v[34:49], v[244:247], v[228:231], v[34:49]
	v_exp_f32_e32 v108, v108
	v_exp_f32_e32 v109, v109
	v_cvt_pk_bf16_f32 v236, v106, v107
	v_add_f32_e32 v17, v17, v89
	ds_read_b64_tr_b16 v[240:241], v210 offset:10368
	ds_read_b64_tr_b16 v[242:243], v210 offset:12928
	ds_read_b64_tr_b16 v[244:245], v210 offset:15488
	ds_read_b64_tr_b16 v[246:247], v210 offset:18048
	s_waitcnt lgkmcnt(14)
	v_mfma_f32_32x32x16_bf16 v[18:33], v[248:251], v[224:227], v[18:33]
	v_exp_f32_e32 v110, v110
	v_exp_f32_e32 v111, v111
	v_cvt_pk_bf16_f32 v237, v108, v109
	v_add_f32_e32 v2, v2, v90
	s_waitcnt lgkmcnt(12)
	v_mfma_f32_32x32x16_bf16 v[18:33], v[252:255], v[228:231], v[18:33]
	v_exp_f32_e32 v112, v112
	v_exp_f32_e32 v113, v113
	v_cvt_pk_bf16_f32 v238, v110, v111
	v_add_f32_e32 v17, v17, v91
	ds_read_b64_tr_b16 v[248:249], v210 offset:10432
	ds_read_b64_tr_b16 v[250:251], v210 offset:12992
	ds_read_b64_tr_b16 v[252:253], v210 offset:15552
	ds_read_b64_tr_b16 v[254:255], v210 offset:18112
	v_cvt_pk_bf16_f32 v239, v112, v113
	s_waitcnt lgkmcnt(14)
	v_mfma_f32_32x32x16_bf16 v[66:81], v[162:165], v[232:235], v[66:81]
	v_add_f32_e32 v2, v2, v92
	v_add_f32_e32 v17, v17, v93
	v_add_f32_e32 v2, v2, v94
	v_add_f32_e32 v17, v17, v95
	s_waitcnt lgkmcnt(12)
	v_mfma_f32_32x32x16_bf16 v[66:81], v[12:15], v[236:239], v[66:81]
	v_add_f32_e32 v2, v2, v96
	v_add_f32_e32 v17, v17, v97
	v_add_f32_e32 v2, v2, v17
	v_add_f32_e32 v16, v98, v99
	s_waitcnt lgkmcnt(10)
	v_mfma_f32_32x32x16_bf16 v[50:65], v[8:11], v[232:235], v[50:65]
	v_add_f32_e32 v223, v100, v101
	v_add_f32_e32 v16, v16, v102
	v_add_f32_e32 v223, v223, v103
	v_add_f32_e32 v16, v16, v104
	s_waitcnt lgkmcnt(8)
	v_mfma_f32_32x32x16_bf16 v[50:65], v[4:7], v[236:239], v[50:65]
	v_add_f32_e32 v223, v223, v105
	v_add_f32_e32 v16, v16, v106
	v_add_f32_e32 v223, v223, v107
	v_add_f32_e32 v16, v16, v108
	s_waitcnt lgkmcnt(6)
	v_mfma_f32_32x32x16_bf16 v[34:49], v[240:243], v[232:235], v[34:49]
	s_mov_b64 s[58:59], 0
	v_add_f32_e32 v223, v223, v109
	v_add_f32_e32 v16, v16, v110
	v_add_f32_e32 v223, v223, v111
	v_add_f32_e32 v16, v16, v112
	s_waitcnt lgkmcnt(4)
	v_mfma_f32_32x32x16_bf16 v[34:49], v[244:247], v[236:239], v[34:49]
	v_add_f32_e32 v223, v223, v113
	v_add_f32_e32 v16, v16, v223
	v_add_f32_e32 v2, v2, v16
	v_add_f32_e32 v168, v168, v2
	s_waitcnt lgkmcnt(2)
	v_mfma_f32_32x32x16_bf16 v[18:33], v[248:251], v[232:235], v[18:33]
	s_waitcnt lgkmcnt(0)
	v_mfma_f32_32x32x16_bf16 v[18:33], v[252:255], v[236:239], v[18:33]
	s_cmp_ge_i32 s85, s81
	s_cbranch_scc1 .LBB0_548

.LBB0_561:
	s_andn2_b64 vcc, exec, s[10:11]
	s_waitcnt lgkmcnt(0)
	s_barrier
	s_cbranch_vccnz .LBB0_563
	ds_read2st64_b32 v[8:9], v211 offset1:1
	ds_read2st64_b32 v[10:11], v211 offset0:2 offset1:3
	ds_read2st64_b32 v[16:17], v211 offset0:4 offset1:5
	ds_read2st64_b32 v[82:83], v211 offset0:6 offset1:7
	v_mov_b32_e32 v168, v66
	v_or_b32_e32 v4, s4, v4
	s_waitcnt lgkmcnt(3)
	v_mov_b32_e32 v7, v8
	v_pk_mul_f32 v[12:13], v[168:169], v[6:7]
	v_mov_b32_e32 v168, v67
	v_mov_b32_e32 v7, v9
	v_pk_mul_f32 v[8:9], v[168:169], v[6:7]
	v_mov_b32_e32 v168, v68
	s_waitcnt lgkmcnt(2)
	v_mov_b32_e32 v7, v10
	v_sub_f32_e32 v14, v8, v9
	v_pk_mul_f32 v[8:9], v[168:169], v[6:7]
	v_mov_b32_e32 v168, v69
	v_mov_b32_e32 v7, v11
	v_pk_mul_f32 v[10:11], v[168:169], v[6:7]
	v_mov_b32_e32 v168, v70
	s_waitcnt lgkmcnt(1)
	v_mov_b32_e32 v7, v16
	v_sub_f32_e32 v8, v8, v9
	v_sub_f32_e32 v9, v10, v11
	v_pk_mul_f32 v[10:11], v[168:169], v[6:7]
	v_mov_b32_e32 v168, v71
	v_mov_b32_e32 v7, v17
	v_sub_f32_e32 v2, v10, v11
	v_pk_mul_f32 v[10:11], v[168:169], v[6:7]
	v_mov_b32_e32 v168, v72
	s_waitcnt lgkmcnt(0)
	v_mov_b32_e32 v7, v82
	v_pk_mul_f32 v[16:17], v[168:169], v[6:7]
	v_mov_b32_e32 v168, v73
	v_mov_b32_e32 v7, v83
	v_sub_f32_e32 v10, v10, v11
	v_sub_f32_e32 v11, v16, v17
	v_pk_mul_f32 v[16:17], v[168:169], v[6:7]
	v_sub_f32_e32 v13, v12, v13
	v_sub_f32_e32 v12, v16, v17
	ds_read2st64_b32 v[16:17], v211 offset0:8 offset1:9
	ds_read2st64_b32 v[72:73], v211 offset0:10 offset1:11
	ds_read2st64_b32 v[82:83], v211 offset0:12 offset1:13
	ds_read2st64_b32 v[84:85], v211 offset0:14 offset1:15
	v_mov_b32_e32 v168, v74
	s_waitcnt lgkmcnt(3)
	v_mov_b32_e32 v7, v16
	v_pk_mul_f32 v[66:67], v[168:169], v[6:7]
	v_mov_b32_e32 v168, v75
	v_mov_b32_e32 v7, v17
	v_pk_mul_f32 v[16:17], v[168:169], v[6:7]
	v_mov_b32_e32 v168, v76
	s_waitcnt lgkmcnt(2)
	v_mov_b32_e32 v7, v72
	v_sub_f32_e32 v70, v16, v17
	v_pk_mul_f32 v[16:17], v[168:169], v[6:7]
	v_mov_b32_e32 v168, v77
	v_mov_b32_e32 v7, v73
	ds_read2st64_b32 v[74:75], v211 offset0:16 offset1:17
	v_sub_f32_e32 v69, v66, v67
	v_sub_f32_e32 v67, v16, v17
	v_pk_mul_f32 v[16:17], v[168:169], v[6:7]
	v_mov_b32_e32 v168, v78
	s_waitcnt lgkmcnt(2)
	v_mov_b32_e32 v7, v82
	v_sub_f32_e32 v68, v16, v17
	v_pk_mul_f32 v[16:17], v[168:169], v[6:7]
	v_mov_b32_e32 v168, v79
	v_mov_b32_e32 v7, v83
	v_sub_f32_e32 v15, v16, v17
	v_pk_mul_f32 v[16:17], v[168:169], v[6:7]
	v_mov_b32_e32 v168, v80
	s_waitcnt lgkmcnt(1)
	v_mov_b32_e32 v7, v84
	v_pk_mul_f32 v[72:73], v[168:169], v[6:7]
	v_mov_b32_e32 v168, v81
	v_mov_b32_e32 v7, v85
	ds_read2st64_b32 v[76:77], v211 offset0:18 offset1:19
	ds_read2st64_b32 v[78:79], v211 offset0:20 offset1:21
	ds_read2st64_b32 v[80:81], v211 offset0:22 offset1:23
	v_sub_f32_e32 v16, v16, v17
	v_sub_f32_e32 v17, v72, v73
	v_pk_mul_f32 v[72:73], v[168:169], v[6:7]
	v_mov_b32_e32 v168, v50
	s_waitcnt lgkmcnt(3)
	v_mov_b32_e32 v7, v74
	v_sub_f32_e32 v66, v72, v73
	v_pk_mul_f32 v[72:73], v[168:169], v[6:7]
	v_mov_b32_e32 v168, v51
	v_mov_b32_e32 v7, v75
	v_pk_mul_f32 v[50:51], v[168:169], v[6:7]
	v_mov_b32_e32 v168, v52
	s_waitcnt lgkmcnt(2)
	v_mov_b32_e32 v7, v76
	v_sub_f32_e32 v74, v50, v51
	v_pk_mul_f32 v[50:51], v[168:169], v[6:7]
	v_mov_b32_e32 v168, v53
	v_mov_b32_e32 v7, v77
	v_sub_f32_e32 v71, v50, v51
	v_pk_mul_f32 v[50:51], v[168:169], v[6:7]
	v_mov_b32_e32 v168, v54
	s_waitcnt lgkmcnt(1)
	v_mov_b32_e32 v7, v78
	v_sub_f32_e32 v73, v72, v73
	v_sub_f32_e32 v72, v50, v51
	v_pk_mul_f32 v[50:51], v[168:169], v[6:7]
	v_mov_b32_e32 v168, v55
	v_mov_b32_e32 v7, v79
	v_pk_mul_f32 v[52:53], v[168:169], v[6:7]
	v_mov_b32_e32 v168, v56
	s_waitcnt lgkmcnt(0)
	v_mov_b32_e32 v7, v80
	v_sub_f32_e32 v50, v50, v51
	v_sub_f32_e32 v51, v52, v53
	v_pk_mul_f32 v[52:53], v[168:169], v[6:7]
	v_mov_b32_e32 v168, v57
	v_mov_b32_e32 v7, v81
	v_pk_mul_f32 v[54:55], v[168:169], v[6:7]
	v_sub_f32_e32 v52, v52, v53
	v_sub_f32_e32 v53, v54, v55
	ds_read2st64_b32 v[54:55], v211 offset0:24 offset1:25
	ds_read2st64_b32 v[56:57], v211 offset0:26 offset1:27
	ds_read2st64_b32 v[78:79], v211 offset0:28 offset1:29
	ds_read2st64_b32 v[80:81], v211 offset0:30 offset1:31
	v_mov_b32_e32 v168, v58
	s_waitcnt lgkmcnt(3)
	v_mov_b32_e32 v7, v54
	v_pk_mul_f32 v[76:77], v[168:169], v[6:7]
	v_mov_b32_e32 v168, v59
	v_mov_b32_e32 v7, v55
	v_pk_mul_f32 v[54:55], v[168:169], v[6:7]
	v_mov_b32_e32 v168, v60
	s_waitcnt lgkmcnt(2)
	v_mov_b32_e32 v7, v56
	v_sub_f32_e32 v75, v76, v77
	v_sub_f32_e32 v76, v54, v55
	v_pk_mul_f32 v[54:55], v[168:169], v[6:7]
	v_mov_b32_e32 v168, v61
	v_mov_b32_e32 v7, v57
	v_sub_f32_e32 v58, v54, v55
	v_pk_mul_f32 v[54:55], v[168:169], v[6:7]
	v_mov_b32_e32 v168, v62
	s_waitcnt lgkmcnt(1)
	v_mov_b32_e32 v7, v78
	v_sub_f32_e32 v59, v54, v55
	v_pk_mul_f32 v[54:55], v[168:169], v[6:7]
	v_mov_b32_e32 v168, v63
	v_mov_b32_e32 v7, v79
	v_pk_mul_f32 v[56:57], v[168:169], v[6:7]
	v_mov_b32_e32 v168, v64
	s_waitcnt lgkmcnt(0)
	v_mov_b32_e32 v7, v80
	v_sub_f32_e32 v54, v54, v55
	v_sub_f32_e32 v55, v56, v57
	v_pk_mul_f32 v[56:57], v[168:169], v[6:7]
	v_mov_b32_e32 v168, v65
	v_mov_b32_e32 v7, v81
	v_pk_mul_f32 v[60:61], v[168:169], v[6:7]
	v_sub_f32_e32 v56, v56, v57
	v_sub_f32_e32 v57, v60, v61
	ds_read2st64_b32 v[60:61], v211 offset0:32 offset1:33
	ds_read2st64_b32 v[64:65], v211 offset0:34 offset1:35
	ds_read2st64_b32 v[78:79], v211 offset0:36 offset1:37
	ds_read2st64_b32 v[80:81], v211 offset0:38 offset1:39
	v_mov_b32_e32 v168, v34
	v_mul_f32_e32 v77, v13, v13
	v_fmac_f32_e32 v77, v14, v14
	s_waitcnt lgkmcnt(3)
	v_mov_b32_e32 v7, v60
	v_pk_mul_f32 v[62:63], v[168:169], v[6:7]
	v_mov_b32_e32 v168, v35
	v_mov_b32_e32 v7, v61
	v_pk_mul_f32 v[34:35], v[168:169], v[6:7]
	v_mov_b32_e32 v168, v36
	s_waitcnt lgkmcnt(2)
	v_mov_b32_e32 v7, v64
	v_sub_f32_e32 v62, v62, v63
	v_sub_f32_e32 v63, v34, v35
	v_pk_mul_f32 v[34:35], v[168:169], v[6:7]
	v_mov_b32_e32 v168, v37
	v_mov_b32_e32 v7, v65
	v_sub_f32_e32 v60, v34, v35
	v_pk_mul_f32 v[34:35], v[168:169], v[6:7]
	v_mov_b32_e32 v168, v38
	s_waitcnt lgkmcnt(1)
	v_mov_b32_e32 v7, v78
	v_sub_f32_e32 v61, v34, v35
	v_pk_mul_f32 v[34:35], v[168:169], v[6:7]
	v_mov_b32_e32 v168, v39
	v_mov_b32_e32 v7, v79
	v_pk_mul_f32 v[36:37], v[168:169], v[6:7]
	v_mov_b32_e32 v168, v40
	s_waitcnt lgkmcnt(0)
	v_mov_b32_e32 v7, v80
	v_sub_f32_e32 v34, v34, v35
	v_sub_f32_e32 v35, v36, v37
	v_pk_mul_f32 v[36:37], v[168:169], v[6:7]
	v_mov_b32_e32 v168, v41
	v_mov_b32_e32 v7, v81
	v_pk_mul_f32 v[38:39], v[168:169], v[6:7]
	v_sub_f32_e32 v36, v36, v37
	v_sub_f32_e32 v37, v38, v39
	ds_read2st64_b32 v[38:39], v211 offset0:40 offset1:41
	ds_read2st64_b32 v[40:41], v211 offset0:42 offset1:43
	ds_read2st64_b32 v[78:79], v211 offset0:44 offset1:45
	ds_read2st64_b32 v[80:81], v211 offset0:46 offset1:47
	v_mov_b32_e32 v168, v42
	v_fmac_f32_e32 v77, v8, v8
	v_fmac_f32_e32 v77, v9, v9
	s_waitcnt lgkmcnt(3)
	v_mov_b32_e32 v7, v38
	v_pk_mul_f32 v[64:65], v[168:169], v[6:7]
	v_mov_b32_e32 v168, v43
	v_mov_b32_e32 v7, v39
	v_pk_mul_f32 v[38:39], v[168:169], v[6:7]
	v_mov_b32_e32 v168, v44
	s_waitcnt lgkmcnt(2)
	v_mov_b32_e32 v7, v40
	v_sub_f32_e32 v64, v64, v65
	v_sub_f32_e32 v65, v38, v39
	v_pk_mul_f32 v[38:39], v[168:169], v[6:7]
	v_mov_b32_e32 v168, v45
	v_mov_b32_e32 v7, v41
	v_sub_f32_e32 v42, v38, v39
	v_pk_mul_f32 v[38:39], v[168:169], v[6:7]
	v_mov_b32_e32 v168, v46
	s_waitcnt lgkmcnt(1)
	v_mov_b32_e32 v7, v78
	v_sub_f32_e32 v43, v38, v39
	v_pk_mul_f32 v[38:39], v[168:169], v[6:7]
	v_mov_b32_e32 v168, v47
	v_mov_b32_e32 v7, v79
	v_pk_mul_f32 v[40:41], v[168:169], v[6:7]
	v_mov_b32_e32 v168, v48
	s_waitcnt lgkmcnt(0)
	v_mov_b32_e32 v7, v80
	v_sub_f32_e32 v38, v38, v39
	v_sub_f32_e32 v39, v40, v41
	v_pk_mul_f32 v[40:41], v[168:169], v[6:7]
	v_mov_b32_e32 v168, v49
	v_mov_b32_e32 v7, v81
	v_pk_mul_f32 v[44:45], v[168:169], v[6:7]
	v_sub_f32_e32 v40, v40, v41
	v_sub_f32_e32 v41, v44, v45
	ds_read2st64_b32 v[44:45], v211 offset0:48 offset1:49
	ds_read2st64_b32 v[48:49], v211 offset0:50 offset1:51
	ds_read2st64_b32 v[78:79], v211 offset0:52 offset1:53
	ds_read2st64_b32 v[80:81], v211 offset0:54 offset1:55
	v_mov_b32_e32 v168, v18
	v_fmac_f32_e32 v77, v2, v2
	v_fmac_f32_e32 v77, v10, v10
	s_waitcnt lgkmcnt(3)
	v_mov_b32_e32 v7, v44
	v_pk_mul_f32 v[46:47], v[168:169], v[6:7]
	v_mov_b32_e32 v168, v19
	v_mov_b32_e32 v7, v45
	v_pk_mul_f32 v[18:19], v[168:169], v[6:7]
	v_mov_b32_e32 v168, v20
	s_waitcnt lgkmcnt(2)
	v_mov_b32_e32 v7, v48
	v_sub_f32_e32 v46, v46, v47
	v_sub_f32_e32 v47, v18, v19
	v_pk_mul_f32 v[18:19], v[168:169], v[6:7]
	v_mov_b32_e32 v168, v21
	v_mov_b32_e32 v7, v49
	v_sub_f32_e32 v44, v18, v19
	v_pk_mul_f32 v[18:19], v[168:169], v[6:7]
	v_mov_b32_e32 v168, v22
	s_waitcnt lgkmcnt(1)
	v_mov_b32_e32 v7, v78
	v_sub_f32_e32 v45, v18, v19
	v_pk_mul_f32 v[18:19], v[168:169], v[6:7]
	v_mov_b32_e32 v168, v23
	v_mov_b32_e32 v7, v79
	v_pk_mul_f32 v[20:21], v[168:169], v[6:7]
	v_mov_b32_e32 v168, v24
	s_waitcnt lgkmcnt(0)
	v_mov_b32_e32 v7, v80
	v_sub_f32_e32 v18, v18, v19
	v_sub_f32_e32 v19, v20, v21
	v_pk_mul_f32 v[20:21], v[168:169], v[6:7]
	v_mov_b32_e32 v168, v25
	v_mov_b32_e32 v7, v81
	v_pk_mul_f32 v[22:23], v[168:169], v[6:7]
	v_fmac_f32_e32 v77, v11, v11
	v_sub_f32_e32 v20, v20, v21
	v_sub_f32_e32 v21, v22, v23
	ds_read2st64_b32 v[22:23], v211 offset0:56 offset1:57
	v_fmac_f32_e32 v77, v12, v12
	v_fmac_f32_e32 v77, v69, v69
	v_fmac_f32_e32 v77, v70, v70
	v_fmac_f32_e32 v77, v67, v67
	ds_read2st64_b32 v[24:25], v211 offset0:58 offset1:59
	ds_read2st64_b32 v[48:49], v211 offset0:60 offset1:61
	ds_read2st64_b32 v[78:79], v211 offset0:62 offset1:63
	v_fmac_f32_e32 v77, v68, v68
	v_mov_b32_e32 v168, v26
	s_waitcnt lgkmcnt(3)
	v_mov_b32_e32 v7, v22
	v_fmac_f32_e32 v77, v15, v15
	v_pk_mul_f32 v[80:81], v[168:169], v[6:7]
	v_mov_b32_e32 v168, v27
	v_mov_b32_e32 v7, v23
	v_fmac_f32_e32 v77, v16, v16
	v_pk_mul_f32 v[22:23], v[168:169], v[6:7]
	v_mov_b32_e32 v168, v28
	s_waitcnt lgkmcnt(2)
	v_mov_b32_e32 v7, v24
	v_fmac_f32_e32 v77, v17, v17
	v_sub_f32_e32 v27, v22, v23
	v_pk_mul_f32 v[22:23], v[168:169], v[6:7]
	v_mov_b32_e32 v168, v29
	v_mov_b32_e32 v7, v25
	v_fmac_f32_e32 v77, v66, v66
	v_sub_f32_e32 v24, v22, v23
	v_pk_mul_f32 v[22:23], v[168:169], v[6:7]
	v_mov_b32_e32 v168, v30
	s_waitcnt lgkmcnt(1)
	v_mov_b32_e32 v7, v48
	v_fmac_f32_e32 v77, v73, v73
	v_sub_f32_e32 v25, v22, v23
	v_pk_mul_f32 v[22:23], v[168:169], v[6:7]
	v_mov_b32_e32 v168, v31
	v_mov_b32_e32 v7, v49
	v_fmac_f32_e32 v77, v74, v74
	v_pk_mul_f32 v[28:29], v[168:169], v[6:7]
	v_fmac_f32_e32 v77, v71, v71
	v_lshlrev_b64 v[48:49], 1, v[4:5]
	v_sub_f32_e32 v22, v22, v23
	v_sub_f32_e32 v23, v28, v29
	s_waitcnt lgkmcnt(0)
	v_pk_mul_f32 v[28:29], v[172:173], v[78:79]
	v_fmac_f32_e32 v77, v72, v72
	v_lshl_add_u64 v[4:5], v[174:175], 0, v[48:49]
	v_pk_fma_f32 v[6:7], v[32:33], v[6:7], v[28:29] op_sel_hi:[1,0,1] neg_lo:[0,0,1] neg_hi:[0,0,1]
	v_fmac_f32_e32 v77, v50, v50
	global_load_dwordx4 v[28:31], v[170:171], off
	global_load_dwordx2 v[78:79], v[4:5], off
	global_load_dwordx4 v[88:91], v[170:171], off offset:32
	global_load_dwordx2 v[148:149], v[4:5], off offset:16
	global_load_dwordx4 v[92:95], v[170:171], off offset:64
	global_load_dwordx2 v[150:151], v[4:5], off offset:32
	global_load_dwordx4 v[96:99], v[170:171], off offset:96
	global_load_dwordx2 v[152:153], v[4:5], off offset:48
	global_load_dwordx4 v[100:103], v[170:171], off offset:128
	global_load_dwordx2 v[154:155], v[4:5], off offset:64
	global_load_dwordx4 v[104:107], v[170:171], off offset:160
	global_load_dwordx2 v[156:157], v[4:5], off offset:80
	global_load_dwordx4 v[108:111], v[170:171], off offset:192
	global_load_dwordx2 v[158:159], v[4:5], off offset:96
	global_load_dwordx4 v[112:115], v[170:171], off offset:224
	global_load_dwordx2 v[160:161], v[4:5], off offset:112
	global_load_dwordx4 v[116:119], v[170:171], off offset:256
	global_load_dwordx2 v[162:163], v[4:5], off offset:128
	global_load_dwordx4 v[120:123], v[170:171], off offset:288
	global_load_dwordx2 v[164:165], v[4:5], off offset:144
	global_load_dwordx4 v[124:127], v[170:171], off offset:320
	global_load_dwordx2 v[86:87], v[4:5], off offset:160
	global_load_dwordx4 v[128:131], v[170:171], off offset:352
	global_load_dwordx2 v[230:231], v[4:5], off offset:176
	global_load_dwordx4 v[132:135], v[170:171], off offset:384
	global_load_dwordx2 v[232:233], v[4:5], off offset:192
	global_load_dwordx4 v[136:139], v[170:171], off offset:416
	global_load_dwordx2 v[234:235], v[4:5], off offset:208
	global_load_dwordx4 v[140:143], v[170:171], off offset:448
	global_load_dwordx2 v[236:237], v[4:5], off offset:224
	global_load_dwordx4 v[144:147], v[170:171], off offset:480
	global_load_dwordx2 v[238:239], v[4:5], off offset:240
	v_fmac_f32_e32 v77, v51, v51
	v_fmac_f32_e32 v77, v52, v52
	v_fmac_f32_e32 v77, v53, v53
	v_fmac_f32_e32 v77, v75, v75
	v_fmac_f32_e32 v77, v76, v76
	v_fmac_f32_e32 v77, v58, v58
	v_fmac_f32_e32 v77, v59, v59
	v_fmac_f32_e32 v77, v54, v54
	v_fmac_f32_e32 v77, v55, v55
	v_fmac_f32_e32 v77, v56, v56
	v_fmac_f32_e32 v77, v57, v57
	v_fmac_f32_e32 v77, v62, v62
	v_fmac_f32_e32 v77, v63, v63
	v_fmac_f32_e32 v77, v60, v60
	v_fmac_f32_e32 v77, v61, v61
	v_fmac_f32_e32 v77, v34, v34
	v_fmac_f32_e32 v77, v35, v35
	v_fmac_f32_e32 v77, v36, v36
	v_fmac_f32_e32 v77, v37, v37
	v_fmac_f32_e32 v77, v64, v64
	v_fmac_f32_e32 v77, v65, v65
	v_fmac_f32_e32 v77, v42, v42
	v_fmac_f32_e32 v77, v43, v43
	v_fmac_f32_e32 v77, v38, v38
	v_fmac_f32_e32 v77, v39, v39
	v_fmac_f32_e32 v77, v40, v40
	v_fmac_f32_e32 v77, v41, v41
	v_fmac_f32_e32 v77, v46, v46
	v_fmac_f32_e32 v77, v47, v47
	v_fmac_f32_e32 v77, v44, v44
	v_fmac_f32_e32 v77, v45, v45
	v_fmac_f32_e32 v77, v18, v18
	v_fmac_f32_e32 v77, v19, v19
	v_fmac_f32_e32 v77, v20, v20
	v_sub_f32_e32 v26, v80, v81
	v_fmac_f32_e32 v77, v21, v21
	v_fmac_f32_e32 v77, v26, v26
	v_fmac_f32_e32 v77, v27, v27
	v_fmac_f32_e32 v77, v24, v24
	v_fmac_f32_e32 v77, v25, v25
	v_fmac_f32_e32 v77, v22, v22
	v_pk_mul_f32 v[32:33], v[6:7], v[6:7]
	v_fmac_f32_e32 v77, v23, v23
	v_add_f32_e32 v32, v77, v32
	v_add_f32_e32 v32, v32, v33
	ds_bpermute_b32 v33, v197, v32
	s_waitcnt lgkmcnt(0)
	v_add_f32_e32 v32, v32, v33
	v_fmamk_f32 v32, v32, 0x3c000000, v214
	v_mul_f32_e32 v33, 0x4f800000, v32
	v_cmp_gt_f32_e32 vcc, s71, v32
	s_nop 1
	v_cndmask_b32_e32 v32, v32, v33, vcc
	v_sqrt_f32_e32 v33, v32
	s_nop 0
	v_add_u32_e32 v77, -1, v33
	v_fma_f32 v80, -v77, v33, v32
	v_cmp_ge_f32_e64 s[4:5], 0, v80
	v_add_u32_e32 v80, 1, v33
	s_nop 0
	v_cndmask_b32_e64 v77, v33, v77, s[4:5]
	v_fma_f32 v33, -v80, v33, v32
	v_cmp_lt_f32_e64 s[4:5], 0, v33
	s_nop 1
	v_cndmask_b32_e64 v33, v77, v80, s[4:5]
	v_mul_f32_e32 v77, 0x37800000, v33
	v_cndmask_b32_e32 v33, v33, v77, vcc
	v_cmp_class_f32_e32 vcc, v32, v200
	s_nop 1
	v_cndmask_b32_e32 v32, v33, v32, vcc
	v_div_scale_f32 v33, s[4:5], v32, v32, s76
	v_rcp_f32_e32 v77, v33
	s_nop 0
	v_fma_f32 v80, -v33, v77, 1.0
	v_fmac_f32_e32 v77, v80, v77
	v_div_scale_f32 v80, vcc, s76, v32, s76
	v_mul_f32_e32 v81, v80, v77
	v_fma_f32 v82, -v33, v81, v80
	v_fmac_f32_e32 v81, v82, v77
	v_fma_f32 v33, -v33, v81, v80
	v_div_fmas_f32 v33, v33, v77, v81
	v_div_fixup_f32 v77, v33, v32, s76
	v_mul_f32_e32 v13, v13, v77
	s_waitcnt vmcnt(31)
	v_mul_f32_e32 v13, v28, v13
	s_waitcnt vmcnt(30)
	v_lshlrev_b32_e32 v28, 16, v78
	v_mul_f32_e32 v14, v14, v77
	v_mul_f32_e32 v13, v13, v28
	v_mul_f32_e32 v14, v29, v14
	v_and_b32_e32 v28, 0xffff0000, v78
	v_mul_f32_e32 v8, v8, v77
	v_mul_f32_e32 v14, v14, v28
	v_cvt_pk_bf16_f32 v28, v13, v14
	v_mul_f32_e32 v8, v30, v8
	v_lshlrev_b32_e32 v13, 16, v79
	v_mul_f32_e32 v9, v9, v77
	v_mul_f32_e32 v8, v8, v13
	v_mul_f32_e32 v9, v31, v9
	v_and_b32_e32 v13, 0xffff0000, v79
	v_mul_f32_e32 v9, v9, v13
	v_cvt_pk_bf16_f32 v29, v8, v9
	v_lshl_add_u64 v[8:9], v[176:177], 0, v[48:49]
	global_store_dwordx2 v[8:9], v[28:29], off
	s_waitcnt vmcnt(29)
	v_mov_b32_e32 v28, v88
	v_mov_b32_e32 v29, v89
	v_mov_b32_e32 v30, v90
	v_mov_b32_e32 v31, v91
	s_nop 0
	v_mov_b32_e32 v32, v148
	v_mov_b32_e32 v33, v149
	v_mul_f32_e32 v2, v2, v77
	v_mul_f32_e32 v10, v10, v77
	v_mul_f32_e32 v6, v6, v77
	v_mul_f32_e32 v7, v7, v77
	v_mul_f32_e32 v2, v28, v2
	v_lshlrev_b32_e32 v13, 16, v32
	v_mul_f32_e32 v2, v2, v13
	v_mul_f32_e32 v10, v29, v10
	v_and_b32_e32 v13, 0xffff0000, v32
	v_mul_f32_e32 v10, v10, v13
	v_cvt_pk_bf16_f32 v10, v2, v10
	v_mul_f32_e32 v2, v11, v77
	v_mul_f32_e32 v2, v30, v2
	v_lshlrev_b32_e32 v11, 16, v33
	v_mul_f32_e32 v2, v2, v11
	v_mul_f32_e32 v11, v12, v77
	v_mul_f32_e32 v11, v31, v11
	v_and_b32_e32 v12, 0xffff0000, v33
	v_mul_f32_e32 v11, v11, v12
	v_cvt_pk_bf16_f32 v11, v2, v11
	global_store_dwordx2 v[8:9], v[10:11], off offset:16
	s_waitcnt vmcnt(28)
	v_mov_b32_e32 v10, v92
	v_mov_b32_e32 v11, v93
	v_mov_b32_e32 v12, v94
	v_mov_b32_e32 v13, v95
	s_nop 0
	v_mov_b32_e32 v28, v150
	v_mov_b32_e32 v29, v151
	v_mul_f32_e32 v2, v69, v77
	v_mul_f32_e32 v2, v2, v10
	v_lshlrev_b32_e32 v10, 16, v28
	v_mul_f32_e32 v2, v2, v10
	v_mul_f32_e32 v10, v70, v77
	v_mul_f32_e32 v10, v10, v11
	v_and_b32_e32 v11, 0xffff0000, v28
	v_mul_f32_e32 v10, v10, v11
	v_cvt_pk_bf16_f32 v10, v2, v10
	v_mul_f32_e32 v2, v67, v77
	v_mul_f32_e32 v2, v2, v12
	v_lshlrev_b32_e32 v11, 16, v29
	v_mul_f32_e32 v2, v2, v11
	v_mul_f32_e32 v11, v68, v77
	v_mul_f32_e32 v11, v11, v13
	v_and_b32_e32 v12, 0xffff0000, v29
	v_mul_f32_e32 v11, v11, v12
	v_cvt_pk_bf16_f32 v11, v2, v11
	global_store_dwordx2 v[8:9], v[10:11], off offset:32
	s_waitcnt vmcnt(27)
	v_mov_b32_e32 v10, v96
	v_mov_b32_e32 v11, v97
	v_mov_b32_e32 v12, v98
	v_mov_b32_e32 v13, v99
	s_nop 0
	v_mov_b32_e32 v28, v152
	v_mov_b32_e32 v29, v153
	v_mul_f32_e32 v2, v15, v77
	v_mul_f32_e32 v2, v2, v10
	v_lshlrev_b32_e32 v10, 16, v28
	v_mul_f32_e32 v2, v2, v10
	v_mul_f32_e32 v10, v16, v77
	v_mul_f32_e32 v10, v10, v11
	v_and_b32_e32 v11, 0xffff0000, v28
	v_mul_f32_e32 v10, v10, v11
	v_cvt_pk_bf16_f32 v10, v2, v10
	v_mul_f32_e32 v2, v17, v77
	v_mul_f32_e32 v2, v2, v12
	v_lshlrev_b32_e32 v11, 16, v29
	v_mul_f32_e32 v2, v2, v11
	v_mul_f32_e32 v11, v66, v77
	v_mul_f32_e32 v11, v11, v13
	v_and_b32_e32 v12, 0xffff0000, v29
	v_mul_f32_e32 v11, v11, v12
	v_cvt_pk_bf16_f32 v11, v2, v11
	global_store_dwordx2 v[8:9], v[10:11], off offset:48
	s_waitcnt vmcnt(26)
	v_mov_b32_e32 v10, v100
	v_mov_b32_e32 v11, v101
	v_mov_b32_e32 v12, v102
	v_mov_b32_e32 v13, v103
	s_nop 0
	v_mov_b32_e32 v14, v154
	v_mov_b32_e32 v15, v155
	v_mul_f32_e32 v2, v73, v77
	v_mul_f32_e32 v16, v51, v77
	v_mul_f32_e32 v17, v52, v77
	v_mul_f32_e32 v28, v53, v77
	v_mul_f32_e32 v2, v2, v10
	v_lshlrev_b32_e32 v10, 16, v14
	v_mul_f32_e32 v2, v2, v10
	v_mul_f32_e32 v10, v74, v77
	v_mul_f32_e32 v10, v10, v11
	v_and_b32_e32 v11, 0xffff0000, v14
	v_mul_f32_e32 v10, v10, v11
	v_cvt_pk_bf16_f32 v10, v2, v10
	v_mul_f32_e32 v2, v71, v77
	v_mul_f32_e32 v2, v2, v12
	v_lshlrev_b32_e32 v11, 16, v15
	v_mul_f32_e32 v2, v2, v11
	v_mul_f32_e32 v11, v72, v77
	v_mul_f32_e32 v11, v11, v13
	v_and_b32_e32 v12, 0xffff0000, v15
	v_mul_f32_e32 v11, v11, v12
	v_cvt_pk_bf16_f32 v11, v2, v11
	global_store_dwordx2 v[8:9], v[10:11], off offset:64
	s_waitcnt vmcnt(25)
	v_mov_b32_e32 v10, v104
	v_mov_b32_e32 v11, v105
	v_mov_b32_e32 v12, v106
	v_mov_b32_e32 v13, v107
	s_nop 0
	v_mov_b32_e32 v14, v156
	v_mov_b32_e32 v15, v157
	v_mul_f32_e32 v2, v50, v77
	v_mul_f32_e32 v2, v2, v10
	v_lshlrev_b32_e32 v10, 16, v14
	v_mul_f32_e32 v11, v16, v11
	v_and_b32_e32 v14, 0xffff0000, v14
	v_mul_f32_e32 v12, v17, v12
	v_lshlrev_b32_e32 v16, 16, v15
	v_mul_f32_e32 v13, v28, v13
	v_and_b32_e32 v15, 0xffff0000, v15
	v_mul_f32_e32 v2, v2, v10
	v_mul_f32_e32 v10, v11, v14
	v_mul_f32_e32 v11, v12, v16
	v_mul_f32_e32 v12, v13, v15
	v_cvt_pk_bf16_f32 v10, v2, v10
	v_cvt_pk_bf16_f32 v11, v11, v12
	global_store_dwordx2 v[8:9], v[10:11], off offset:80
	s_waitcnt vmcnt(24)
	v_mov_b32_e32 v10, v108
	v_mov_b32_e32 v11, v109
	v_mov_b32_e32 v12, v110
	v_mov_b32_e32 v13, v111
	s_nop 0
	v_mov_b32_e32 v14, v158
	v_mov_b32_e32 v15, v159
	v_mul_f32_e32 v2, v75, v77
	v_mul_f32_e32 v16, v76, v77
	v_mul_f32_e32 v17, v58, v77
	v_mul_f32_e32 v28, v59, v77
	v_mul_f32_e32 v2, v2, v10
	v_lshlrev_b32_e32 v10, 16, v14
	v_mul_f32_e32 v11, v16, v11
	v_and_b32_e32 v14, 0xffff0000, v14
	v_mul_f32_e32 v12, v17, v12
	v_lshlrev_b32_e32 v16, 16, v15
	v_mul_f32_e32 v13, v28, v13
	v_and_b32_e32 v15, 0xffff0000, v15
	v_mul_f32_e32 v2, v2, v10
	v_mul_f32_e32 v10, v11, v14
	v_mul_f32_e32 v11, v12, v16
	v_mul_f32_e32 v12, v13, v15
	v_cvt_pk_bf16_f32 v10, v2, v10
	v_cvt_pk_bf16_f32 v11, v11, v12
	global_store_dwordx2 v[8:9], v[10:11], off offset:96
	s_waitcnt vmcnt(23)
	v_mov_b32_e32 v10, v112
	v_mov_b32_e32 v11, v113
	v_mov_b32_e32 v12, v114
	v_mov_b32_e32 v13, v115
	s_nop 0
	v_mov_b32_e32 v14, v160
	v_mov_b32_e32 v15, v161
	v_mul_f32_e32 v2, v54, v77
	v_mul_f32_e32 v16, v55, v77
	v_mul_f32_e32 v17, v56, v77
	v_mul_f32_e32 v28, v57, v77
	v_mul_f32_e32 v2, v2, v10
	v_lshlrev_b32_e32 v10, 16, v14
	v_mul_f32_e32 v11, v16, v11
	v_and_b32_e32 v14, 0xffff0000, v14
	v_mul_f32_e32 v12, v17, v12
	v_lshlrev_b32_e32 v16, 16, v15
	v_mul_f32_e32 v13, v28, v13
	v_and_b32_e32 v15, 0xffff0000, v15
	v_mul_f32_e32 v2, v2, v10
	v_mul_f32_e32 v10, v11, v14
	v_mul_f32_e32 v11, v12, v16
	v_mul_f32_e32 v12, v13, v15
	v_cvt_pk_bf16_f32 v10, v2, v10
	v_cvt_pk_bf16_f32 v11, v11, v12
	global_store_dwordx2 v[8:9], v[10:11], off offset:112
	s_waitcnt vmcnt(22)
	v_mov_b32_e32 v10, v116
	v_mov_b32_e32 v11, v117
	v_mov_b32_e32 v12, v118
	v_mov_b32_e32 v13, v119
	s_nop 0
	v_mov_b32_e32 v14, v162
	v_mov_b32_e32 v15, v163
	v_mul_f32_e32 v2, v62, v77
	v_mul_f32_e32 v16, v63, v77
	v_mul_f32_e32 v17, v60, v77
	v_mul_f32_e32 v28, v61, v77
	v_mul_f32_e32 v2, v2, v10
	v_lshlrev_b32_e32 v10, 16, v14
	v_mul_f32_e32 v11, v16, v11
	v_and_b32_e32 v14, 0xffff0000, v14
	v_mul_f32_e32 v12, v17, v12
	v_lshlrev_b32_e32 v16, 16, v15
	v_mul_f32_e32 v13, v28, v13
	v_and_b32_e32 v15, 0xffff0000, v15
	v_mul_f32_e32 v2, v2, v10
	v_mul_f32_e32 v10, v11, v14
	v_mul_f32_e32 v11, v12, v16
	v_mul_f32_e32 v12, v13, v15
	v_cvt_pk_bf16_f32 v10, v2, v10
	v_cvt_pk_bf16_f32 v11, v11, v12
	global_store_dwordx2 v[8:9], v[10:11], off offset:128
	s_waitcnt vmcnt(21)
	v_mov_b32_e32 v10, v120
	v_mov_b32_e32 v11, v121
	v_mov_b32_e32 v12, v122
	v_mov_b32_e32 v13, v123
	s_nop 0
	v_mov_b32_e32 v14, v164
	v_mov_b32_e32 v15, v165
	v_mul_f32_e32 v2, v34, v77
	v_mul_f32_e32 v16, v35, v77
	v_mul_f32_e32 v17, v36, v77
	v_mul_f32_e32 v28, v37, v77
	v_mul_f32_e32 v2, v2, v10
	v_lshlrev_b32_e32 v10, 16, v14
	v_mul_f32_e32 v11, v16, v11
	v_and_b32_e32 v14, 0xffff0000, v14
	v_mul_f32_e32 v12, v17, v12
	v_lshlrev_b32_e32 v16, 16, v15
	v_mul_f32_e32 v13, v28, v13
	v_and_b32_e32 v15, 0xffff0000, v15
	v_mul_f32_e32 v2, v2, v10
	v_mul_f32_e32 v10, v11, v14
	v_mul_f32_e32 v11, v12, v16
	v_mul_f32_e32 v12, v13, v15
	v_cvt_pk_bf16_f32 v10, v2, v10
	v_cvt_pk_bf16_f32 v11, v11, v12
	global_store_dwordx2 v[8:9], v[10:11], off offset:144
	s_waitcnt vmcnt(20)
	v_mov_b32_e32 v10, v124
	v_mov_b32_e32 v11, v125
	v_mov_b32_e32 v12, v126
	v_mov_b32_e32 v13, v127
	s_nop 0
	v_mov_b32_e32 v14, v86
	v_mov_b32_e32 v15, v87
	v_mul_f32_e32 v2, v64, v77
	v_mul_f32_e32 v16, v65, v77
	v_mul_f32_e32 v17, v42, v77
	v_mul_f32_e32 v28, v43, v77
	v_mul_f32_e32 v2, v2, v10
	v_lshlrev_b32_e32 v10, 16, v14
	v_mul_f32_e32 v11, v16, v11
	v_and_b32_e32 v14, 0xffff0000, v14
	v_mul_f32_e32 v12, v17, v12
	v_lshlrev_b32_e32 v16, 16, v15
	v_mul_f32_e32 v13, v28, v13
	v_and_b32_e32 v15, 0xffff0000, v15
	v_mul_f32_e32 v2, v2, v10
	v_mul_f32_e32 v10, v11, v14
	v_mul_f32_e32 v11, v12, v16
	v_mul_f32_e32 v12, v13, v15
	v_cvt_pk_bf16_f32 v10, v2, v10
	v_cvt_pk_bf16_f32 v11, v11, v12
	global_store_dwordx2 v[8:9], v[10:11], off offset:160
	s_waitcnt vmcnt(19)
	v_mov_b32_e32 v10, v128
	v_mov_b32_e32 v11, v129
	v_mov_b32_e32 v12, v130
	v_mov_b32_e32 v13, v131
	s_nop 0
	v_mov_b32_e32 v14, v230
	v_mov_b32_e32 v15, v231
	v_mul_f32_e32 v2, v38, v77
	v_mul_f32_e32 v16, v39, v77
	v_mul_f32_e32 v17, v40, v77
	v_mul_f32_e32 v28, v41, v77
	v_mul_f32_e32 v2, v2, v10
	v_lshlrev_b32_e32 v10, 16, v14
	v_mul_f32_e32 v11, v16, v11
	v_and_b32_e32 v14, 0xffff0000, v14
	v_mul_f32_e32 v12, v17, v12
	v_lshlrev_b32_e32 v16, 16, v15
	v_mul_f32_e32 v13, v28, v13
	v_and_b32_e32 v15, 0xffff0000, v15
	v_mul_f32_e32 v2, v2, v10
	v_mul_f32_e32 v10, v11, v14
	v_mul_f32_e32 v11, v12, v16
	v_mul_f32_e32 v12, v13, v15
	v_cvt_pk_bf16_f32 v10, v2, v10
	v_cvt_pk_bf16_f32 v11, v11, v12
	global_store_dwordx2 v[8:9], v[10:11], off offset:176
	s_waitcnt vmcnt(18)
	v_mov_b32_e32 v10, v132
	v_mov_b32_e32 v11, v133
	v_mov_b32_e32 v12, v134
	v_mov_b32_e32 v13, v135
	s_nop 0
	v_mov_b32_e32 v14, v232
	v_mov_b32_e32 v15, v233
	v_mul_f32_e32 v2, v46, v77
	v_mul_f32_e32 v16, v47, v77
	v_mul_f32_e32 v17, v44, v77
	v_mul_f32_e32 v28, v45, v77
	v_mul_f32_e32 v2, v2, v10
	v_lshlrev_b32_e32 v10, 16, v14
	v_mul_f32_e32 v11, v16, v11
	v_and_b32_e32 v14, 0xffff0000, v14
	v_mul_f32_e32 v12, v17, v12
	v_lshlrev_b32_e32 v16, 16, v15
	v_mul_f32_e32 v13, v28, v13
	v_and_b32_e32 v15, 0xffff0000, v15
	v_mul_f32_e32 v2, v2, v10
	v_mul_f32_e32 v10, v11, v14
	v_mul_f32_e32 v11, v12, v16
	v_mul_f32_e32 v12, v13, v15
	v_cvt_pk_bf16_f32 v10, v2, v10
	v_cvt_pk_bf16_f32 v11, v11, v12
	global_store_dwordx2 v[8:9], v[10:11], off offset:192
	s_waitcnt vmcnt(17)
	v_mov_b32_e32 v10, v136
	v_mov_b32_e32 v11, v137
	v_mov_b32_e32 v12, v138
	v_mov_b32_e32 v13, v139
	s_nop 0
	v_mov_b32_e32 v14, v234
	v_mov_b32_e32 v15, v235
	v_mul_f32_e32 v2, v18, v77
	v_mul_f32_e32 v16, v19, v77
	v_mul_f32_e32 v17, v20, v77
	v_mul_f32_e32 v18, v21, v77
	v_mul_f32_e32 v2, v2, v10
	v_lshlrev_b32_e32 v10, 16, v14
	v_mul_f32_e32 v11, v16, v11
	v_and_b32_e32 v14, 0xffff0000, v14
	v_mul_f32_e32 v12, v17, v12
	v_lshlrev_b32_e32 v16, 16, v15
	v_mul_f32_e32 v13, v18, v13
	v_and_b32_e32 v15, 0xffff0000, v15
	v_mul_f32_e32 v2, v2, v10
	v_mul_f32_e32 v10, v11, v14
	v_mul_f32_e32 v11, v12, v16
	v_mul_f32_e32 v12, v13, v15
	v_cvt_pk_bf16_f32 v10, v2, v10
	v_cvt_pk_bf16_f32 v11, v11, v12
	global_store_dwordx2 v[8:9], v[10:11], off offset:208
	s_waitcnt vmcnt(16)
	v_mov_b32_e32 v10, v140
	v_mov_b32_e32 v11, v141
	v_mov_b32_e32 v12, v142
	v_mov_b32_e32 v13, v143
	s_nop 0
	v_mov_b32_e32 v14, v236
	v_mov_b32_e32 v15, v237
	v_mul_f32_e32 v2, v26, v77
	v_mul_f32_e32 v16, v27, v77
	v_mul_f32_e32 v17, v24, v77
	v_mul_f32_e32 v18, v25, v77
	v_mul_f32_e32 v2, v2, v10
	v_lshlrev_b32_e32 v10, 16, v14
	v_mul_f32_e32 v11, v16, v11
	v_and_b32_e32 v14, 0xffff0000, v14
	v_mul_f32_e32 v12, v17, v12
	v_lshlrev_b32_e32 v16, 16, v15
	v_mul_f32_e32 v13, v18, v13
	v_and_b32_e32 v15, 0xffff0000, v15
	v_mul_f32_e32 v2, v2, v10
	v_mul_f32_e32 v10, v11, v14
	v_mul_f32_e32 v11, v12, v16
	v_mul_f32_e32 v12, v13, v15
	v_cvt_pk_bf16_f32 v10, v2, v10
	v_cvt_pk_bf16_f32 v11, v11, v12
	global_store_dwordx2 v[8:9], v[10:11], off offset:224
	s_waitcnt vmcnt(15)
	v_mov_b32_e32 v10, v144
	v_mov_b32_e32 v11, v145
	v_mov_b32_e32 v12, v146
	v_mov_b32_e32 v13, v147
	s_nop 0
	v_mov_b32_e32 v4, v238
	v_mov_b32_e32 v5, v239
	v_mul_f32_e32 v2, v22, v77
	v_mul_f32_e32 v14, v23, v77
	v_mul_f32_e32 v2, v2, v10
	v_lshlrev_b32_e32 v10, 16, v4
	v_mul_f32_e32 v11, v14, v11
	v_and_b32_e32 v4, 0xffff0000, v4
	v_mul_f32_e32 v6, v6, v12
	v_lshlrev_b32_e32 v12, 16, v5
	v_mul_f32_e32 v7, v7, v13
	v_and_b32_e32 v5, 0xffff0000, v5
	v_mul_f32_e32 v4, v11, v4
	v_mul_f32_e32 v5, v7, v5
	v_mul_f32_e32 v2, v2, v10
	v_mul_f32_e32 v6, v6, v12
	v_cvt_pk_bf16_f32 v4, v2, v4
	v_cvt_pk_bf16_f32 v5, v6, v5
	global_store_dwordx2 v[8:9], v[4:5], off offset:240

	.amdhsa_kernel _Z8fwd_mega4Args
		.amdhsa_group_segment_fixed_size 0
		.amdhsa_private_segment_fixed_size 0
		.amdhsa_kernarg_size 456
		.amdhsa_user_sgpr_count 2
		.amdhsa_user_sgpr_dispatch_ptr 0
		.amdhsa_user_sgpr_queue_ptr 0
		.amdhsa_user_sgpr_kernarg_segment_ptr 1
		.amdhsa_user_sgpr_dispatch_id 0
		.amdhsa_user_sgpr_kernarg_preload_length 0
		.amdhsa_user_sgpr_kernarg_preload_offset 0
		.amdhsa_user_sgpr_private_segment_size 0
		.amdhsa_uses_dynamic_stack 0
		.amdhsa_enable_private_segment 0
		.amdhsa_system_sgpr_workgroup_id_x 1
		.amdhsa_system_sgpr_workgroup_id_y 0
		.amdhsa_system_sgpr_workgroup_id_z 0
		.amdhsa_system_sgpr_workgroup_info 0
		.amdhsa_system_vgpr_workitem_id 2
		.amdhsa_next_free_vgpr 256
		.amdhsa_next_free_sgpr 97
		.amdhsa_accum_offset 256
		.amdhsa_reserve_vcc 1
		.amdhsa_float_round_mode_32 0
		.amdhsa_float_round_mode_16_64 0
		.amdhsa_float_denorm_mode_32 3
		.amdhsa_float_denorm_mode_16_64 3
		.amdhsa_dx10_clamp 1
		.amdhsa_ieee_mode 1
		.amdhsa_fp16_overflow 0
		.amdhsa_tg_split 0
		.amdhsa_exception_fp_ieee_invalid_op 0
		.amdhsa_exception_fp_denorm_src 0
		.amdhsa_exception_fp_ieee_div_zero 0
		.amdhsa_exception_fp_ieee_overflow 0
		.amdhsa_exception_fp_ieee_underflow 0
		.amdhsa_exception_fp_ieee_inexact 0
		.amdhsa_exception_int_div_zero 0
	.end_amdhsa_kernel

amdhsa.kernels:
  - .agpr_count:     0
    .args:
      - .offset:         0
        .size:           200
        .value_kind:     by_value
      - .offset:         200
        .size:           4
        .value_kind:     hidden_block_count_x
      - .offset:         204
        .size:           4
        .value_kind:     hidden_block_count_y
      - .offset:         208
        .size:           4
        .value_kind:     hidden_block_count_z
      - .offset:         212
        .size:           2
        .value_kind:     hidden_group_size_x
      - .offset:         214
        .size:           2
        .value_kind:     hidden_group_size_y
      - .offset:         216
        .size:           2
        .value_kind:     hidden_group_size_z
      - .offset:         218
        .size:           2
        .value_kind:     hidden_remainder_x
      - .offset:         220
        .size:           2
        .value_kind:     hidden_remainder_y
      - .offset:         222
        .size:           2
        .value_kind:     hidden_remainder_z
      - .offset:         240
        .size:           8
        .value_kind:     hidden_global_offset_x
      - .offset:         248
        .size:           8
        .value_kind:     hidden_global_offset_y
      - .offset:         256
        .size:           8
        .value_kind:     hidden_global_offset_z
      - .offset:         264
        .size:           2
        .value_kind:     hidden_grid_dims
      - .offset:         288
        .size:           8
        .value_kind:     hidden_multigrid_sync_arg
      - .offset:         320
        .size:           4
        .value_kind:     hidden_dynamic_lds_size
    .group_segment_fixed_size: 0
    .kernarg_segment_align: 8
    .kernarg_segment_size: 456
    .language:       OpenCL C
    .language_version:
      - 2
      - 0
    .max_flat_workgroup_size: 512
    .name:           _Z8fwd_mega4Args
    .private_segment_fixed_size: 0
    .sgpr_count:     103
    .sgpr_spill_count: 0
    .symbol:         _Z8fwd_mega4Args.kd
    .uniform_work_group_size: 1
    .uses_dynamic_stack: false
    .vgpr_count:     256
    .vgpr_spill_count: 0
    .wavefront_size: 64
